# v023 + NSA top-16 rank loop stops after the last candidate key chunk (trip count from c)
# speedup vs baseline: 1.0158x; 1.0069x over previous
; __device__ __forceinline__ void nsa_unit(const int wv, LAS unsigned char* lds, int b, int g, int c, const bf16* Y, const bf16* KCMP, const bf16* VCMP, const float* gates, bf16* OG) {
;     ...
;             int cnt[8]; unsigned long long mykey[8];
; #pragma unroll
;             for (int e = 0; e < 8; ++e) { cnt[e] = 0; mykey[e] = keys[tk * 66 + 8 * sub + e]; }
; #pragma unroll 4
;             for (int ch = 0; ch < 16; ++ch) {
;                 unsigned long long k4[4];
; #pragma unroll
;                 for (int i = 0; i < 4; ++i) k4[i] = keys[tk * 66 + 4 * ch + i];
; #pragma unroll
;                 for (int i = 0; i < 4; ++i)
; #pragma unroll
;                     for (int e = 0; e < 8; ++e) cnt[e] += (k4[i] > mykey[e]) ? 1 : 0;
;             }
.LBB0_898:
	s_or_b64 exec, exec, s[4:5]
	v_readlane_b32 s0, v254, 42
	v_readlane_b32 s1, v254, 43
	s_andn2_b64 vcc, exec, s[0:1]
	s_mov_b64 s[4:5], -1
	ds_write_b64 v44, v[32:33] offset:56
	s_waitcnt lgkmcnt(0)
	s_barrier
	s_cbranch_vccnz .LBB0_910
	v_lshl_add_u32 v44, v50, 6, v53
	ds_read_b128 v[32:35], v44
	ds_read_b128 v[36:39], v44 offset:16
	ds_read_b128 v[40:43], v44 offset:32
	ds_read_b128 v[44:47], v44 offset:48
	s_mov_b32 s4, 0
	s_add_i32 s5, s38, -2
	s_lshr_b32 s5, s5, 4
	s_lshl_b32 s5, s5, 7
	s_addk_i32 s5, 0x80
	v_mov_b32_e32 v66, 0
	v_mov_b32_e32 v65, 0
	v_mov_b32_e32 v64, 0
	v_mov_b32_e32 v63, 0
	v_mov_b32_e32 v62, 0
	v_mov_b32_e32 v61, 0
	v_mov_b32_e32 v60, 0
	v_mov_b32_e32 v59, 0
.LBB0_900:
	s_waitcnt vmcnt(0)
	v_add_u32_e32 v84, s4, v53
	ds_read_b128 v[68:71], v84
	ds_read_b128 v[72:75], v84 offset:16
	ds_read_b128 v[76:79], v84 offset:32
	ds_read_b128 v[80:83], v84 offset:48
	s_addk_i32 s4, 0x80
	s_waitcnt lgkmcnt(3)
	v_cmp_gt_u64_e32 vcc, v[68:69], v[32:33]
	s_cmp_eq_u32 s4, s5
	s_nop 0
	v_cndmask_b32_e64 v67, 0, 1, vcc
	v_cmp_gt_u64_e32 vcc, v[68:69], v[34:35]
	s_nop 1
	v_cndmask_b32_e64 v85, 0, 1, vcc
	v_cmp_gt_u64_e32 vcc, v[68:69], v[36:37]
	s_waitcnt vmcnt(0)
	s_nop 0
	v_cndmask_b32_e64 v86, 0, 1, vcc
	v_cmp_gt_u64_e32 vcc, v[68:69], v[38:39]
	s_nop 1
	v_cndmask_b32_e64 v87, 0, 1, vcc
	v_cmp_gt_u64_e32 vcc, v[68:69], v[40:41]
	s_nop 1
	v_cndmask_b32_e64 v88, 0, 1, vcc
	v_cmp_gt_u64_e32 vcc, v[68:69], v[42:43]
	s_nop 1
	v_cndmask_b32_e64 v89, 0, 1, vcc
	v_cmp_gt_u64_e32 vcc, v[68:69], v[44:45]
	s_nop 1
	v_cndmask_b32_e64 v90, 0, 1, vcc
	v_cmp_gt_u64_e32 vcc, v[68:69], v[46:47]
	s_nop 1
	v_cndmask_b32_e64 v68, 0, 1, vcc
	v_cmp_gt_u64_e32 vcc, v[70:71], v[32:33]
	s_nop 1
	v_addc_co_u32_e32 v66, vcc, v66, v67, vcc
	v_cmp_gt_u64_e32 vcc, v[70:71], v[34:35]
	s_nop 1
	v_addc_co_u32_e32 v65, vcc, v65, v85, vcc
	v_cmp_gt_u64_e32 vcc, v[70:71], v[36:37]
	s_nop 1
	v_addc_co_u32_e32 v64, vcc, v64, v86, vcc
	v_cmp_gt_u64_e32 vcc, v[70:71], v[38:39]
	s_nop 1
	v_addc_co_u32_e32 v63, vcc, v63, v87, vcc
	v_cmp_gt_u64_e32 vcc, v[70:71], v[40:41]
	s_nop 1
	v_addc_co_u32_e32 v62, vcc, v62, v88, vcc
	v_cmp_gt_u64_e32 vcc, v[70:71], v[42:43]
	s_nop 1
	v_addc_co_u32_e32 v61, vcc, v61, v89, vcc
	v_cmp_gt_u64_e32 vcc, v[70:71], v[44:45]
	s_nop 1
	v_addc_co_u32_e32 v60, vcc, v60, v90, vcc
	v_cmp_gt_u64_e32 vcc, v[70:71], v[46:47]
	s_nop 1
	v_addc_co_u32_e32 v59, vcc, v59, v68, vcc
	s_waitcnt lgkmcnt(2)
	v_cmp_gt_u64_e32 vcc, v[72:73], v[32:33]
	s_nop 1
	v_cndmask_b32_e64 v67, 0, 1, vcc
	v_cmp_gt_u64_e32 vcc, v[72:73], v[34:35]
	s_nop 1
	v_cndmask_b32_e64 v68, 0, 1, vcc
	v_cmp_gt_u64_e32 vcc, v[72:73], v[36:37]
	s_nop 1
	v_cndmask_b32_e64 v69, 0, 1, vcc
	v_cmp_gt_u64_e32 vcc, v[72:73], v[38:39]
	s_nop 1
	v_cndmask_b32_e64 v70, 0, 1, vcc
	v_cmp_gt_u64_e32 vcc, v[72:73], v[40:41]
	s_nop 1
	v_cndmask_b32_e64 v71, 0, 1, vcc
	v_cmp_gt_u64_e32 vcc, v[72:73], v[42:43]
	s_nop 1
	v_cndmask_b32_e64 v85, 0, 1, vcc
	v_cmp_gt_u64_e32 vcc, v[72:73], v[44:45]
	s_nop 1
	v_cndmask_b32_e64 v86, 0, 1, vcc
	v_cmp_gt_u64_e32 vcc, v[72:73], v[46:47]
	s_nop 1
	v_cndmask_b32_e64 v72, 0, 1, vcc
	v_cmp_gt_u64_e32 vcc, v[74:75], v[32:33]
	s_nop 1
	v_addc_co_u32_e32 v66, vcc, v66, v67, vcc
	v_cmp_gt_u64_e32 vcc, v[74:75], v[34:35]
	s_nop 1
	v_addc_co_u32_e32 v65, vcc, v65, v68, vcc
	v_cmp_gt_u64_e32 vcc, v[74:75], v[36:37]
	s_nop 1
	v_addc_co_u32_e32 v64, vcc, v64, v69, vcc
	v_cmp_gt_u64_e32 vcc, v[74:75], v[38:39]
	s_nop 1
	v_addc_co_u32_e32 v63, vcc, v63, v70, vcc
	v_cmp_gt_u64_e32 vcc, v[74:75], v[40:41]
	s_nop 1
	v_addc_co_u32_e32 v62, vcc, v62, v71, vcc
	v_cmp_gt_u64_e32 vcc, v[74:75], v[42:43]
	s_nop 1
	v_addc_co_u32_e32 v61, vcc, v61, v85, vcc
	v_cmp_gt_u64_e32 vcc, v[74:75], v[44:45]
	s_nop 1
	v_addc_co_u32_e32 v60, vcc, v60, v86, vcc
	v_cmp_gt_u64_e32 vcc, v[74:75], v[46:47]
	s_nop 1
	v_addc_co_u32_e32 v59, vcc, v59, v72, vcc
	s_waitcnt lgkmcnt(1)
	v_cmp_gt_u64_e32 vcc, v[76:77], v[32:33]
	s_nop 1
	v_cndmask_b32_e64 v67, 0, 1, vcc
	v_cmp_gt_u64_e32 vcc, v[76:77], v[34:35]
	s_nop 1
	v_cndmask_b32_e64 v68, 0, 1, vcc
	v_cmp_gt_u64_e32 vcc, v[76:77], v[36:37]
	s_nop 1
	v_cndmask_b32_e64 v69, 0, 1, vcc
	v_cmp_gt_u64_e32 vcc, v[76:77], v[38:39]
	s_nop 1
	v_cndmask_b32_e64 v70, 0, 1, vcc
	v_cmp_gt_u64_e32 vcc, v[76:77], v[40:41]
	s_nop 1
	v_cndmask_b32_e64 v71, 0, 1, vcc
	v_cmp_gt_u64_e32 vcc, v[76:77], v[42:43]
	s_nop 1
	v_cndmask_b32_e64 v72, 0, 1, vcc
	v_cmp_gt_u64_e32 vcc, v[76:77], v[44:45]
	s_nop 1
	v_cndmask_b32_e64 v73, 0, 1, vcc
	v_cmp_gt_u64_e32 vcc, v[76:77], v[46:47]
	s_nop 1
	v_cndmask_b32_e64 v74, 0, 1, vcc
	v_cmp_gt_u64_e32 vcc, v[78:79], v[32:33]
	s_nop 1
	v_addc_co_u32_e32 v66, vcc, v66, v67, vcc
	v_cmp_gt_u64_e32 vcc, v[78:79], v[34:35]
	s_nop 1
	v_addc_co_u32_e32 v65, vcc, v65, v68, vcc
	v_cmp_gt_u64_e32 vcc, v[78:79], v[36:37]
	s_nop 1
	v_addc_co_u32_e32 v64, vcc, v64, v69, vcc
	v_cmp_gt_u64_e32 vcc, v[78:79], v[38:39]
	s_nop 1
	v_addc_co_u32_e32 v63, vcc, v63, v70, vcc
	v_cmp_gt_u64_e32 vcc, v[78:79], v[40:41]
	s_nop 1
	v_addc_co_u32_e32 v62, vcc, v62, v71, vcc
	v_cmp_gt_u64_e32 vcc, v[78:79], v[42:43]
	s_nop 1
	v_addc_co_u32_e32 v61, vcc, v61, v72, vcc
	v_cmp_gt_u64_e32 vcc, v[78:79], v[44:45]
	s_nop 1
	v_addc_co_u32_e32 v60, vcc, v60, v73, vcc
	v_cmp_gt_u64_e32 vcc, v[78:79], v[46:47]
	s_nop 1
	v_addc_co_u32_e32 v59, vcc, v59, v74, vcc
	s_waitcnt lgkmcnt(0)
; __device__ __forceinline__ void nsa_unit(const int wv, LAS unsigned char* lds, int b, int g, int c, const bf16* Y, const bf16* KCMP, const bf16* VCMP, const float* gates, bf16* OG) {
;     ...
;             for (int ch = 0; ch < 16; ++ch) {
;                 unsigned long long k4[4];
; #pragma unroll
;                 for (int i = 0; i < 4; ++i) k4[i] = keys[tk * 66 + 4 * ch + i];
; #pragma unroll
;                 for (int i = 0; i < 4; ++i)
; #pragma unroll
;                     for (int e = 0; e < 8; ++e) cnt[e] += (k4[i] > mykey[e]) ? 1 : 0;
;             }
	v_cmp_gt_u64_e32 vcc, v[80:81], v[32:33]
	s_nop 1
	v_cndmask_b32_e64 v67, 0, 1, vcc
	v_cmp_gt_u64_e32 vcc, v[80:81], v[34:35]
	s_nop 1
	v_cndmask_b32_e64 v68, 0, 1, vcc
	v_cmp_gt_u64_e32 vcc, v[80:81], v[36:37]
	s_nop 1
	v_cndmask_b32_e64 v69, 0, 1, vcc
	v_cmp_gt_u64_e32 vcc, v[80:81], v[38:39]
	s_nop 1
	v_cndmask_b32_e64 v70, 0, 1, vcc
	v_cmp_gt_u64_e32 vcc, v[80:81], v[40:41]
	s_nop 1
	v_cndmask_b32_e64 v71, 0, 1, vcc
	v_cmp_gt_u64_e32 vcc, v[80:81], v[42:43]
	s_nop 1
	v_cndmask_b32_e64 v72, 0, 1, vcc
	v_cmp_gt_u64_e32 vcc, v[80:81], v[44:45]
	s_nop 1
	v_cndmask_b32_e64 v73, 0, 1, vcc
	v_cmp_gt_u64_e32 vcc, v[80:81], v[46:47]
	s_nop 1
	v_cndmask_b32_e64 v74, 0, 1, vcc
	v_cmp_gt_u64_e32 vcc, v[82:83], v[32:33]
	s_nop 1
	v_addc_co_u32_e32 v75, vcc, v66, v67, vcc
	v_cmp_gt_u64_e32 vcc, v[82:83], v[34:35]
	s_nop 1
	v_addc_co_u32_e32 v68, vcc, v65, v68, vcc
	v_cmp_gt_u64_e32 vcc, v[82:83], v[36:37]
	s_nop 1
	v_addc_co_u32_e32 v69, vcc, v64, v69, vcc
	v_cmp_gt_u64_e32 vcc, v[82:83], v[38:39]
	s_nop 1
	v_addc_co_u32_e32 v70, vcc, v63, v70, vcc
	v_cmp_gt_u64_e32 vcc, v[82:83], v[40:41]
	s_nop 1
	v_addc_co_u32_e32 v71, vcc, v62, v71, vcc
	v_cmp_gt_u64_e32 vcc, v[82:83], v[42:43]
	s_nop 1
	v_addc_co_u32_e32 v72, vcc, v61, v72, vcc
	v_cmp_gt_u64_e32 vcc, v[82:83], v[44:45]
	s_nop 1
	v_addc_co_u32_e32 v73, vcc, v60, v73, vcc
	ds_read_b128 v[60:63], v84 offset:64
	ds_read_b128 v[64:67], v84 offset:80
	v_cmp_gt_u64_e32 vcc, v[82:83], v[46:47]
	s_nop 1
	v_addc_co_u32_e32 v59, vcc, v59, v74, vcc
	s_waitcnt lgkmcnt(1)
	v_cmp_gt_u64_e32 vcc, v[60:61], v[32:33]
	s_nop 1
	v_cndmask_b32_e64 v74, 0, 1, vcc
	v_cmp_gt_u64_e32 vcc, v[60:61], v[34:35]
	s_nop 1
	v_cndmask_b32_e64 v76, 0, 1, vcc
	v_cmp_gt_u64_e32 vcc, v[60:61], v[36:37]
	s_nop 1
	v_cndmask_b32_e64 v77, 0, 1, vcc
	v_cmp_gt_u64_e32 vcc, v[60:61], v[38:39]
	s_nop 1
	v_cndmask_b32_e64 v78, 0, 1, vcc
	v_cmp_gt_u64_e32 vcc, v[60:61], v[40:41]
	s_nop 1
	v_cndmask_b32_e64 v79, 0, 1, vcc
	v_cmp_gt_u64_e32 vcc, v[60:61], v[42:43]
	s_nop 1
	v_cndmask_b32_e64 v80, 0, 1, vcc
	v_cmp_gt_u64_e32 vcc, v[60:61], v[44:45]
	s_nop 1
	v_cndmask_b32_e64 v81, 0, 1, vcc
	v_cmp_gt_u64_e32 vcc, v[60:61], v[46:47]
	s_nop 1
	v_cndmask_b32_e64 v60, 0, 1, vcc
	v_cmp_gt_u64_e32 vcc, v[62:63], v[32:33]
	s_nop 1
	v_addc_co_u32_e32 v61, vcc, v75, v74, vcc
	v_cmp_gt_u64_e32 vcc, v[62:63], v[34:35]
	s_nop 1
	v_addc_co_u32_e32 v68, vcc, v68, v76, vcc
	v_cmp_gt_u64_e32 vcc, v[62:63], v[36:37]
	s_nop 1
	v_addc_co_u32_e32 v69, vcc, v69, v77, vcc
	v_cmp_gt_u64_e32 vcc, v[62:63], v[38:39]
	s_nop 1
	v_addc_co_u32_e32 v70, vcc, v70, v78, vcc
	v_cmp_gt_u64_e32 vcc, v[62:63], v[40:41]
	s_nop 1
	v_addc_co_u32_e32 v71, vcc, v71, v79, vcc
	v_cmp_gt_u64_e32 vcc, v[62:63], v[42:43]
	s_nop 1
	v_addc_co_u32_e32 v72, vcc, v72, v80, vcc
	v_cmp_gt_u64_e32 vcc, v[62:63], v[44:45]
	s_nop 1
	v_addc_co_u32_e32 v73, vcc, v73, v81, vcc
	v_cmp_gt_u64_e32 vcc, v[62:63], v[46:47]
	s_nop 1
	v_addc_co_u32_e32 v59, vcc, v59, v60, vcc
	s_waitcnt lgkmcnt(0)
	v_cmp_gt_u64_e32 vcc, v[64:65], v[32:33]
	s_nop 1
	v_cndmask_b32_e64 v60, 0, 1, vcc
	v_cmp_gt_u64_e32 vcc, v[64:65], v[34:35]
	s_nop 1
	v_cndmask_b32_e64 v62, 0, 1, vcc
	v_cmp_gt_u64_e32 vcc, v[64:65], v[36:37]
	s_nop 1
	v_cndmask_b32_e64 v63, 0, 1, vcc
	v_cmp_gt_u64_e32 vcc, v[64:65], v[38:39]
	s_nop 1
	v_cndmask_b32_e64 v74, 0, 1, vcc
	v_cmp_gt_u64_e32 vcc, v[64:65], v[40:41]
	s_nop 1
	v_cndmask_b32_e64 v75, 0, 1, vcc
	v_cmp_gt_u64_e32 vcc, v[64:65], v[42:43]
	s_nop 1
	v_cndmask_b32_e64 v76, 0, 1, vcc
	v_cmp_gt_u64_e32 vcc, v[64:65], v[44:45]
	s_nop 1
	v_cndmask_b32_e64 v77, 0, 1, vcc
	v_cmp_gt_u64_e32 vcc, v[64:65], v[46:47]
	s_nop 1
	v_cndmask_b32_e64 v64, 0, 1, vcc
	v_cmp_gt_u64_e32 vcc, v[66:67], v[32:33]
	s_nop 1
	v_addc_co_u32_e32 v65, vcc, v61, v60, vcc
	v_cmp_gt_u64_e32 vcc, v[66:67], v[34:35]
	s_nop 1
	v_addc_co_u32_e32 v78, vcc, v68, v62, vcc
	v_cmp_gt_u64_e32 vcc, v[66:67], v[36:37]
	s_nop 1
	v_addc_co_u32_e32 v79, vcc, v69, v63, vcc
	v_cmp_gt_u64_e32 vcc, v[66:67], v[38:39]
	s_nop 1
	v_addc_co_u32_e32 v70, vcc, v70, v74, vcc
	v_cmp_gt_u64_e32 vcc, v[66:67], v[40:41]
	s_nop 1
	v_addc_co_u32_e32 v71, vcc, v71, v75, vcc
	v_cmp_gt_u64_e32 vcc, v[66:67], v[42:43]
	s_nop 1
	v_addc_co_u32_e32 v72, vcc, v72, v76, vcc
	v_cmp_gt_u64_e32 vcc, v[66:67], v[44:45]
	s_nop 1
	v_addc_co_u32_e32 v73, vcc, v73, v77, vcc
	v_cmp_gt_u64_e32 vcc, v[66:67], v[46:47]
	ds_read_b128 v[60:63], v84 offset:96
	ds_read_b128 v[66:69], v84 offset:112
	v_addc_co_u32_e32 v59, vcc, v59, v64, vcc
	s_waitcnt lgkmcnt(1)
; __device__ __forceinline__ void nsa_unit(const int wv, LAS unsigned char* lds, int b, int g, int c, const bf16* Y, const bf16* KCMP, const bf16* VCMP, const float* gates, bf16* OG) {
;     ...
;             }
; #pragma unroll
;             for (int e = 0; e < 8; ++e) { const int s = 8 * sub + e;
;                 if (s == 0 || s == c || s == c - 1) bits |= (1u << e);
;                 else if (s < c - 1 && cnt[e] < 13) bits |= (1u << e); }
	v_cmp_gt_u64_e32 vcc, v[60:61], v[32:33]
	s_nop 1
	v_cndmask_b32_e64 v64, 0, 1, vcc
	v_cmp_gt_u64_e32 vcc, v[60:61], v[34:35]
	s_nop 1
	v_cndmask_b32_e64 v74, 0, 1, vcc
	v_cmp_gt_u64_e32 vcc, v[60:61], v[36:37]
	s_nop 1
	v_cndmask_b32_e64 v75, 0, 1, vcc
	v_cmp_gt_u64_e32 vcc, v[60:61], v[38:39]
	s_nop 1
	v_cndmask_b32_e64 v76, 0, 1, vcc
	v_cmp_gt_u64_e32 vcc, v[60:61], v[40:41]
	s_nop 1
	v_cndmask_b32_e64 v77, 0, 1, vcc
	v_cmp_gt_u64_e32 vcc, v[60:61], v[42:43]
	s_nop 1
	v_cndmask_b32_e64 v80, 0, 1, vcc
	v_cmp_gt_u64_e32 vcc, v[60:61], v[44:45]
	s_nop 1
	v_cndmask_b32_e64 v81, 0, 1, vcc
	v_cmp_gt_u64_e32 vcc, v[60:61], v[46:47]
	s_nop 1
	v_cndmask_b32_e64 v60, 0, 1, vcc
	v_cmp_gt_u64_e32 vcc, v[62:63], v[32:33]
	s_nop 1
	v_addc_co_u32_e32 v61, vcc, v65, v64, vcc
	v_cmp_gt_u64_e32 vcc, v[62:63], v[34:35]
	s_nop 1
	v_addc_co_u32_e32 v64, vcc, v78, v74, vcc
	v_cmp_gt_u64_e32 vcc, v[62:63], v[36:37]
	s_nop 1
	v_addc_co_u32_e32 v74, vcc, v79, v75, vcc
	v_cmp_gt_u64_e32 vcc, v[62:63], v[38:39]
	s_nop 1
	v_addc_co_u32_e32 v70, vcc, v70, v76, vcc
	v_cmp_gt_u64_e32 vcc, v[62:63], v[40:41]
	s_nop 1
	v_addc_co_u32_e32 v71, vcc, v71, v77, vcc
	v_cmp_gt_u64_e32 vcc, v[62:63], v[42:43]
	s_nop 1
	v_addc_co_u32_e32 v72, vcc, v72, v80, vcc
	v_cmp_gt_u64_e32 vcc, v[62:63], v[44:45]
	s_nop 1
	v_addc_co_u32_e32 v73, vcc, v73, v81, vcc
	v_cmp_gt_u64_e32 vcc, v[62:63], v[46:47]
	s_nop 1
	v_addc_co_u32_e32 v59, vcc, v59, v60, vcc
	s_waitcnt lgkmcnt(0)
	v_cmp_gt_u64_e32 vcc, v[66:67], v[32:33]
	s_nop 1
	v_cndmask_b32_e64 v60, 0, 1, vcc
	v_cmp_gt_u64_e32 vcc, v[66:67], v[34:35]
	s_nop 1
	v_cndmask_b32_e64 v62, 0, 1, vcc
	v_cmp_gt_u64_e32 vcc, v[66:67], v[36:37]
	s_nop 1
	v_cndmask_b32_e64 v63, 0, 1, vcc
	v_cmp_gt_u64_e32 vcc, v[66:67], v[38:39]
	s_nop 1
	v_cndmask_b32_e64 v75, 0, 1, vcc
	v_cmp_gt_u64_e32 vcc, v[66:67], v[40:41]
	s_nop 1
	v_cndmask_b32_e64 v76, 0, 1, vcc
	v_cmp_gt_u64_e32 vcc, v[66:67], v[42:43]
	s_nop 1
	v_cndmask_b32_e64 v77, 0, 1, vcc
	v_cmp_gt_u64_e32 vcc, v[66:67], v[44:45]
	s_nop 1
	v_cndmask_b32_e64 v78, 0, 1, vcc
	v_cmp_gt_u64_e32 vcc, v[66:67], v[46:47]
	s_nop 1
	v_cndmask_b32_e64 v67, 0, 1, vcc
	v_cmp_gt_u64_e32 vcc, v[68:69], v[32:33]
	s_nop 1
	v_addc_co_u32_e32 v66, vcc, v61, v60, vcc
	v_cmp_gt_u64_e32 vcc, v[68:69], v[34:35]
	s_nop 1
	v_addc_co_u32_e32 v65, vcc, v64, v62, vcc
	v_cmp_gt_u64_e32 vcc, v[68:69], v[36:37]
	s_nop 1
	v_addc_co_u32_e32 v64, vcc, v74, v63, vcc
	v_cmp_gt_u64_e32 vcc, v[68:69], v[38:39]
	s_nop 1
	v_addc_co_u32_e32 v63, vcc, v70, v75, vcc
	v_cmp_gt_u64_e32 vcc, v[68:69], v[40:41]
	s_nop 1
	v_addc_co_u32_e32 v62, vcc, v71, v76, vcc
	v_cmp_gt_u64_e32 vcc, v[68:69], v[42:43]
	s_nop 1
	v_addc_co_u32_e32 v61, vcc, v72, v77, vcc
	v_cmp_gt_u64_e32 vcc, v[68:69], v[44:45]
	s_nop 1
	v_addc_co_u32_e32 v60, vcc, v73, v78, vcc
	v_cmp_gt_u64_e32 vcc, v[68:69], v[46:47]
	s_nop 1
	v_addc_co_u32_e32 v59, vcc, v59, v67, vcc
	s_cbranch_scc0 .LBB0_900
	v_cmp_eq_u32_e32 vcc, 0, v50
	v_cmp_eq_u32_e64 s[6:7], s38, v51
	v_readlane_b32 s8, v254, 44
	s_or_b64 s[0:1], vcc, s[6:7]
	v_cmp_gt_i32_e64 s[6:7], 13, v66
	v_cmp_eq_u32_e32 vcc, s8, v51
	s_or_b64 s[0:1], s[0:1], vcc
	v_cmp_gt_u32_e32 vcc, s8, v51
	v_or_b32_e32 v34, 1, v51
	s_and_b64 s[4:5], vcc, s[6:7]
	s_or_b64 s[0:1], s[0:1], s[4:5]
	v_cmp_ne_u32_e32 vcc, s38, v34
	v_cmp_ne_u32_e64 s[6:7], s8, v34
	v_cndmask_b32_e64 v33, 0, 1, s[0:1]
	s_and_b64 s[0:1], vcc, s[6:7]
	s_and_saveexec_b64 s[4:5], s[0:1]
	s_xor_b64 s[4:5], exec, s[4:5]
	s_cbranch_execz .LBB0_903
	v_readlane_b32 s0, v254, 44
	v_cmp_gt_i32_e64 s[6:7], 13, v65
	s_nop 0
	v_cmp_gt_u32_e32 vcc, s0, v34
	s_and_b64 s[0:1], vcc, s[6:7]
	v_cndmask_b32_e64 v32, 0, 2, s[0:1]
	v_or_b32_e32 v32, v32, v33

; __device__ __forceinline__ void nsa_unit(const int wv, LAS unsigned char* lds, int b, int g, int c, const bf16* Y, const bf16* KCMP, const bf16* VCMP, const float* gates, bf16* OG) {
;     ...
;             int cnt[8]; unsigned long long mykey[8];
; #pragma unroll
;             for (int e = 0; e < 8; ++e) { cnt[e] = 0; mykey[e] = keys[tk * 66 + 8 * sub + e]; }
; #pragma unroll 4
;             for (int ch = 0; ch < 16; ++ch) {
;                 unsigned long long k4[4];
; #pragma unroll
;                 for (int i = 0; i < 4; ++i) k4[i] = keys[tk * 66 + 4 * ch + i];
; #pragma unroll
;                 for (int i = 0; i < 4; ++i)
; #pragma unroll
;                     for (int e = 0; e < 8; ++e) cnt[e] += (k4[i] > mykey[e]) ? 1 : 0;
;             }
.LBB0_1054:
	s_or_b64 exec, exec, s[4:5]
	v_readlane_b32 s0, v255, 0
	v_readlane_b32 s1, v255, 1
	s_andn2_b64 vcc, exec, s[0:1]
	s_mov_b64 s[4:5], -1
	ds_write_b64 v44, v[32:33] offset:56
	s_waitcnt lgkmcnt(0)
	s_barrier
	s_cbranch_vccnz .LBB0_1066
	v_lshl_add_u32 v44, v50, 6, v53
	ds_read_b128 v[32:35], v44
	ds_read_b128 v[36:39], v44 offset:16
	ds_read_b128 v[40:43], v44 offset:32
	ds_read_b128 v[44:47], v44 offset:48
	s_mov_b32 s4, 0
	s_add_i32 s5, s39, -2
	s_lshr_b32 s5, s5, 4
	s_lshl_b32 s5, s5, 7
	s_addk_i32 s5, 0x80
	v_mov_b32_e32 v66, 0
	v_mov_b32_e32 v65, 0
	v_mov_b32_e32 v64, 0
	v_mov_b32_e32 v63, 0
	v_mov_b32_e32 v62, 0
	v_mov_b32_e32 v61, 0
	v_mov_b32_e32 v60, 0
	v_mov_b32_e32 v59, 0
.LBB0_1056:
	s_waitcnt vmcnt(1)
	v_add_u32_e32 v84, s4, v53
	ds_read_b128 v[68:71], v84
	ds_read_b128 v[72:75], v84 offset:16
	ds_read_b128 v[76:79], v84 offset:32
	ds_read_b128 v[80:83], v84 offset:48
	s_addk_i32 s4, 0x80
	s_waitcnt lgkmcnt(3)
	v_cmp_gt_u64_e32 vcc, v[68:69], v[32:33]
	s_cmp_eq_u32 s4, s5
	s_nop 0
	v_cndmask_b32_e64 v67, 0, 1, vcc
	v_cmp_gt_u64_e32 vcc, v[68:69], v[34:35]
	s_nop 1
	v_cndmask_b32_e64 v85, 0, 1, vcc
	v_cmp_gt_u64_e32 vcc, v[68:69], v[36:37]
	s_waitcnt vmcnt(0)
	s_nop 0
	v_cndmask_b32_e64 v86, 0, 1, vcc
	v_cmp_gt_u64_e32 vcc, v[68:69], v[38:39]
	s_nop 1
	v_cndmask_b32_e64 v87, 0, 1, vcc
	v_cmp_gt_u64_e32 vcc, v[68:69], v[40:41]
	s_nop 1
	v_cndmask_b32_e64 v88, 0, 1, vcc
	v_cmp_gt_u64_e32 vcc, v[68:69], v[42:43]
	s_nop 1
	v_cndmask_b32_e64 v89, 0, 1, vcc
	v_cmp_gt_u64_e32 vcc, v[68:69], v[44:45]
	s_nop 1
	v_cndmask_b32_e64 v90, 0, 1, vcc
	v_cmp_gt_u64_e32 vcc, v[68:69], v[46:47]
	s_nop 1
	v_cndmask_b32_e64 v68, 0, 1, vcc
	v_cmp_gt_u64_e32 vcc, v[70:71], v[32:33]
	s_nop 1
	v_addc_co_u32_e32 v66, vcc, v66, v67, vcc
	v_cmp_gt_u64_e32 vcc, v[70:71], v[34:35]
	s_nop 1
	v_addc_co_u32_e32 v65, vcc, v65, v85, vcc
	v_cmp_gt_u64_e32 vcc, v[70:71], v[36:37]
	s_nop 1
	v_addc_co_u32_e32 v64, vcc, v64, v86, vcc
	v_cmp_gt_u64_e32 vcc, v[70:71], v[38:39]
	s_nop 1
	v_addc_co_u32_e32 v63, vcc, v63, v87, vcc
	v_cmp_gt_u64_e32 vcc, v[70:71], v[40:41]
	s_nop 1
	v_addc_co_u32_e32 v62, vcc, v62, v88, vcc
	v_cmp_gt_u64_e32 vcc, v[70:71], v[42:43]
	s_nop 1
	v_addc_co_u32_e32 v61, vcc, v61, v89, vcc
	v_cmp_gt_u64_e32 vcc, v[70:71], v[44:45]
	s_nop 1
	v_addc_co_u32_e32 v60, vcc, v60, v90, vcc
	v_cmp_gt_u64_e32 vcc, v[70:71], v[46:47]
	s_nop 1
	v_addc_co_u32_e32 v59, vcc, v59, v68, vcc
	s_waitcnt lgkmcnt(2)
	v_cmp_gt_u64_e32 vcc, v[72:73], v[32:33]
	s_nop 1
	v_cndmask_b32_e64 v67, 0, 1, vcc
	v_cmp_gt_u64_e32 vcc, v[72:73], v[34:35]
	s_nop 1
	v_cndmask_b32_e64 v68, 0, 1, vcc
	v_cmp_gt_u64_e32 vcc, v[72:73], v[36:37]
	s_nop 1
	v_cndmask_b32_e64 v69, 0, 1, vcc
	v_cmp_gt_u64_e32 vcc, v[72:73], v[38:39]
	s_nop 1
	v_cndmask_b32_e64 v70, 0, 1, vcc
	v_cmp_gt_u64_e32 vcc, v[72:73], v[40:41]
	s_nop 1
	v_cndmask_b32_e64 v71, 0, 1, vcc
	v_cmp_gt_u64_e32 vcc, v[72:73], v[42:43]
	s_nop 1
	v_cndmask_b32_e64 v85, 0, 1, vcc
	v_cmp_gt_u64_e32 vcc, v[72:73], v[44:45]
	s_nop 1
	v_cndmask_b32_e64 v86, 0, 1, vcc
	v_cmp_gt_u64_e32 vcc, v[72:73], v[46:47]
	s_nop 1
	v_cndmask_b32_e64 v72, 0, 1, vcc
	v_cmp_gt_u64_e32 vcc, v[74:75], v[32:33]
	s_nop 1
	v_addc_co_u32_e32 v66, vcc, v66, v67, vcc
	v_cmp_gt_u64_e32 vcc, v[74:75], v[34:35]
	s_nop 1
	v_addc_co_u32_e32 v65, vcc, v65, v68, vcc
	v_cmp_gt_u64_e32 vcc, v[74:75], v[36:37]
	s_nop 1
	v_addc_co_u32_e32 v64, vcc, v64, v69, vcc
	v_cmp_gt_u64_e32 vcc, v[74:75], v[38:39]
	s_nop 1
	v_addc_co_u32_e32 v63, vcc, v63, v70, vcc
	v_cmp_gt_u64_e32 vcc, v[74:75], v[40:41]
	s_nop 1
	v_addc_co_u32_e32 v62, vcc, v62, v71, vcc
	v_cmp_gt_u64_e32 vcc, v[74:75], v[42:43]
	s_nop 1
	v_addc_co_u32_e32 v61, vcc, v61, v85, vcc
	v_cmp_gt_u64_e32 vcc, v[74:75], v[44:45]
	s_nop 1
	v_addc_co_u32_e32 v60, vcc, v60, v86, vcc
	v_cmp_gt_u64_e32 vcc, v[74:75], v[46:47]
	s_nop 1
	v_addc_co_u32_e32 v59, vcc, v59, v72, vcc
	s_waitcnt lgkmcnt(1)
	v_cmp_gt_u64_e32 vcc, v[76:77], v[32:33]
	s_nop 1
	v_cndmask_b32_e64 v67, 0, 1, vcc
	v_cmp_gt_u64_e32 vcc, v[76:77], v[34:35]
	s_nop 1
	v_cndmask_b32_e64 v68, 0, 1, vcc
	v_cmp_gt_u64_e32 vcc, v[76:77], v[36:37]
	s_nop 1
	v_cndmask_b32_e64 v69, 0, 1, vcc
	v_cmp_gt_u64_e32 vcc, v[76:77], v[38:39]
	s_nop 1
	v_cndmask_b32_e64 v70, 0, 1, vcc
	v_cmp_gt_u64_e32 vcc, v[76:77], v[40:41]
	s_nop 1
	v_cndmask_b32_e64 v71, 0, 1, vcc
	v_cmp_gt_u64_e32 vcc, v[76:77], v[42:43]
	s_nop 1
	v_cndmask_b32_e64 v72, 0, 1, vcc
	v_cmp_gt_u64_e32 vcc, v[76:77], v[44:45]
	s_nop 1
	v_cndmask_b32_e64 v73, 0, 1, vcc
	v_cmp_gt_u64_e32 vcc, v[76:77], v[46:47]
	s_nop 1
	v_cndmask_b32_e64 v74, 0, 1, vcc
	v_cmp_gt_u64_e32 vcc, v[78:79], v[32:33]
	s_nop 1
	v_addc_co_u32_e32 v66, vcc, v66, v67, vcc
	v_cmp_gt_u64_e32 vcc, v[78:79], v[34:35]
	s_nop 1
	v_addc_co_u32_e32 v65, vcc, v65, v68, vcc
	v_cmp_gt_u64_e32 vcc, v[78:79], v[36:37]
	s_nop 1
	v_addc_co_u32_e32 v64, vcc, v64, v69, vcc
	v_cmp_gt_u64_e32 vcc, v[78:79], v[38:39]
	s_nop 1
	v_addc_co_u32_e32 v63, vcc, v63, v70, vcc
	v_cmp_gt_u64_e32 vcc, v[78:79], v[40:41]
	s_nop 1
	v_addc_co_u32_e32 v62, vcc, v62, v71, vcc
	v_cmp_gt_u64_e32 vcc, v[78:79], v[42:43]
	s_nop 1
	v_addc_co_u32_e32 v61, vcc, v61, v72, vcc
	v_cmp_gt_u64_e32 vcc, v[78:79], v[44:45]
	s_nop 1
	v_addc_co_u32_e32 v60, vcc, v60, v73, vcc
	v_cmp_gt_u64_e32 vcc, v[78:79], v[46:47]
	s_nop 1
	v_addc_co_u32_e32 v59, vcc, v59, v74, vcc
	s_waitcnt lgkmcnt(0)
; __device__ __forceinline__ void nsa_unit(const int wv, LAS unsigned char* lds, int b, int g, int c, const bf16* Y, const bf16* KCMP, const bf16* VCMP, const float* gates, bf16* OG) {
;     ...
;             for (int ch = 0; ch < 16; ++ch) {
;                 unsigned long long k4[4];
; #pragma unroll
;                 for (int i = 0; i < 4; ++i) k4[i] = keys[tk * 66 + 4 * ch + i];
; #pragma unroll
;                 for (int i = 0; i < 4; ++i)
; #pragma unroll
;                     for (int e = 0; e < 8; ++e) cnt[e] += (k4[i] > mykey[e]) ? 1 : 0;
;             }
	v_cmp_gt_u64_e32 vcc, v[80:81], v[32:33]
	s_nop 1
	v_cndmask_b32_e64 v67, 0, 1, vcc
	v_cmp_gt_u64_e32 vcc, v[80:81], v[34:35]
	s_nop 1
	v_cndmask_b32_e64 v68, 0, 1, vcc
	v_cmp_gt_u64_e32 vcc, v[80:81], v[36:37]
	s_nop 1
	v_cndmask_b32_e64 v69, 0, 1, vcc
	v_cmp_gt_u64_e32 vcc, v[80:81], v[38:39]
	s_nop 1
	v_cndmask_b32_e64 v70, 0, 1, vcc
	v_cmp_gt_u64_e32 vcc, v[80:81], v[40:41]
	s_nop 1
	v_cndmask_b32_e64 v71, 0, 1, vcc
	v_cmp_gt_u64_e32 vcc, v[80:81], v[42:43]
	s_nop 1
	v_cndmask_b32_e64 v72, 0, 1, vcc
	v_cmp_gt_u64_e32 vcc, v[80:81], v[44:45]
	s_nop 1
	v_cndmask_b32_e64 v73, 0, 1, vcc
	v_cmp_gt_u64_e32 vcc, v[80:81], v[46:47]
	s_nop 1
	v_cndmask_b32_e64 v74, 0, 1, vcc
	v_cmp_gt_u64_e32 vcc, v[82:83], v[32:33]
	s_nop 1
	v_addc_co_u32_e32 v75, vcc, v66, v67, vcc
	v_cmp_gt_u64_e32 vcc, v[82:83], v[34:35]
	s_nop 1
	v_addc_co_u32_e32 v68, vcc, v65, v68, vcc
	v_cmp_gt_u64_e32 vcc, v[82:83], v[36:37]
	s_nop 1
	v_addc_co_u32_e32 v69, vcc, v64, v69, vcc
	v_cmp_gt_u64_e32 vcc, v[82:83], v[38:39]
	s_nop 1
	v_addc_co_u32_e32 v70, vcc, v63, v70, vcc
	v_cmp_gt_u64_e32 vcc, v[82:83], v[40:41]
	s_nop 1
	v_addc_co_u32_e32 v71, vcc, v62, v71, vcc
	v_cmp_gt_u64_e32 vcc, v[82:83], v[42:43]
	s_nop 1
	v_addc_co_u32_e32 v72, vcc, v61, v72, vcc
	v_cmp_gt_u64_e32 vcc, v[82:83], v[44:45]
	s_nop 1
	v_addc_co_u32_e32 v73, vcc, v60, v73, vcc
	ds_read_b128 v[60:63], v84 offset:64
	ds_read_b128 v[64:67], v84 offset:80
	v_cmp_gt_u64_e32 vcc, v[82:83], v[46:47]
	s_nop 1
	v_addc_co_u32_e32 v59, vcc, v59, v74, vcc
	s_waitcnt lgkmcnt(1)
	v_cmp_gt_u64_e32 vcc, v[60:61], v[32:33]
	s_nop 1
	v_cndmask_b32_e64 v74, 0, 1, vcc
	v_cmp_gt_u64_e32 vcc, v[60:61], v[34:35]
	s_nop 1
	v_cndmask_b32_e64 v76, 0, 1, vcc
	v_cmp_gt_u64_e32 vcc, v[60:61], v[36:37]
	s_nop 1
	v_cndmask_b32_e64 v77, 0, 1, vcc
	v_cmp_gt_u64_e32 vcc, v[60:61], v[38:39]
	s_nop 1
	v_cndmask_b32_e64 v78, 0, 1, vcc
	v_cmp_gt_u64_e32 vcc, v[60:61], v[40:41]
	s_nop 1
	v_cndmask_b32_e64 v79, 0, 1, vcc
	v_cmp_gt_u64_e32 vcc, v[60:61], v[42:43]
	s_nop 1
	v_cndmask_b32_e64 v80, 0, 1, vcc
	v_cmp_gt_u64_e32 vcc, v[60:61], v[44:45]
	s_nop 1
	v_cndmask_b32_e64 v81, 0, 1, vcc
	v_cmp_gt_u64_e32 vcc, v[60:61], v[46:47]
	s_nop 1
	v_cndmask_b32_e64 v60, 0, 1, vcc
	v_cmp_gt_u64_e32 vcc, v[62:63], v[32:33]
	s_nop 1
	v_addc_co_u32_e32 v61, vcc, v75, v74, vcc
	v_cmp_gt_u64_e32 vcc, v[62:63], v[34:35]
	s_nop 1
	v_addc_co_u32_e32 v68, vcc, v68, v76, vcc
	v_cmp_gt_u64_e32 vcc, v[62:63], v[36:37]
	s_nop 1
	v_addc_co_u32_e32 v69, vcc, v69, v77, vcc
	v_cmp_gt_u64_e32 vcc, v[62:63], v[38:39]
	s_nop 1
	v_addc_co_u32_e32 v70, vcc, v70, v78, vcc
	v_cmp_gt_u64_e32 vcc, v[62:63], v[40:41]
	s_nop 1
	v_addc_co_u32_e32 v71, vcc, v71, v79, vcc
	v_cmp_gt_u64_e32 vcc, v[62:63], v[42:43]
	s_nop 1
	v_addc_co_u32_e32 v72, vcc, v72, v80, vcc
	v_cmp_gt_u64_e32 vcc, v[62:63], v[44:45]
	s_nop 1
	v_addc_co_u32_e32 v73, vcc, v73, v81, vcc
	v_cmp_gt_u64_e32 vcc, v[62:63], v[46:47]
	s_nop 1
	v_addc_co_u32_e32 v59, vcc, v59, v60, vcc
	s_waitcnt lgkmcnt(0)
	v_cmp_gt_u64_e32 vcc, v[64:65], v[32:33]
	s_nop 1
	v_cndmask_b32_e64 v60, 0, 1, vcc
	v_cmp_gt_u64_e32 vcc, v[64:65], v[34:35]
	s_nop 1
	v_cndmask_b32_e64 v62, 0, 1, vcc
	v_cmp_gt_u64_e32 vcc, v[64:65], v[36:37]
	s_nop 1
	v_cndmask_b32_e64 v63, 0, 1, vcc
	v_cmp_gt_u64_e32 vcc, v[64:65], v[38:39]
	s_nop 1
	v_cndmask_b32_e64 v74, 0, 1, vcc
	v_cmp_gt_u64_e32 vcc, v[64:65], v[40:41]
	s_nop 1
	v_cndmask_b32_e64 v75, 0, 1, vcc
	v_cmp_gt_u64_e32 vcc, v[64:65], v[42:43]
	s_nop 1
	v_cndmask_b32_e64 v76, 0, 1, vcc
	v_cmp_gt_u64_e32 vcc, v[64:65], v[44:45]
	s_nop 1
	v_cndmask_b32_e64 v77, 0, 1, vcc
	v_cmp_gt_u64_e32 vcc, v[64:65], v[46:47]
	s_nop 1
	v_cndmask_b32_e64 v64, 0, 1, vcc
	v_cmp_gt_u64_e32 vcc, v[66:67], v[32:33]
	s_nop 1
	v_addc_co_u32_e32 v65, vcc, v61, v60, vcc
	v_cmp_gt_u64_e32 vcc, v[66:67], v[34:35]
	s_nop 1
	v_addc_co_u32_e32 v78, vcc, v68, v62, vcc
	v_cmp_gt_u64_e32 vcc, v[66:67], v[36:37]
	s_nop 1
	v_addc_co_u32_e32 v79, vcc, v69, v63, vcc
	v_cmp_gt_u64_e32 vcc, v[66:67], v[38:39]
	s_nop 1
	v_addc_co_u32_e32 v70, vcc, v70, v74, vcc
	v_cmp_gt_u64_e32 vcc, v[66:67], v[40:41]
	s_nop 1
	v_addc_co_u32_e32 v71, vcc, v71, v75, vcc
	v_cmp_gt_u64_e32 vcc, v[66:67], v[42:43]
	s_nop 1
	v_addc_co_u32_e32 v72, vcc, v72, v76, vcc
	v_cmp_gt_u64_e32 vcc, v[66:67], v[44:45]
	s_nop 1
	v_addc_co_u32_e32 v73, vcc, v73, v77, vcc
	v_cmp_gt_u64_e32 vcc, v[66:67], v[46:47]
	ds_read_b128 v[60:63], v84 offset:96
	ds_read_b128 v[66:69], v84 offset:112
	v_addc_co_u32_e32 v59, vcc, v59, v64, vcc
	s_waitcnt lgkmcnt(1)
; __device__ __forceinline__ void nsa_unit(const int wv, LAS unsigned char* lds, int b, int g, int c, const bf16* Y, const bf16* KCMP, const bf16* VCMP, const float* gates, bf16* OG) {
;     ...
;             }
; #pragma unroll
;             for (int e = 0; e < 8; ++e) { const int s = 8 * sub + e;
;                 if (s == 0 || s == c || s == c - 1) bits |= (1u << e);
;                 else if (s < c - 1 && cnt[e] < 13) bits |= (1u << e); }
	v_cmp_gt_u64_e32 vcc, v[60:61], v[32:33]
	s_nop 1
	v_cndmask_b32_e64 v64, 0, 1, vcc
	v_cmp_gt_u64_e32 vcc, v[60:61], v[34:35]
	s_nop 1
	v_cndmask_b32_e64 v74, 0, 1, vcc
	v_cmp_gt_u64_e32 vcc, v[60:61], v[36:37]
	s_nop 1
	v_cndmask_b32_e64 v75, 0, 1, vcc
	v_cmp_gt_u64_e32 vcc, v[60:61], v[38:39]
	s_nop 1
	v_cndmask_b32_e64 v76, 0, 1, vcc
	v_cmp_gt_u64_e32 vcc, v[60:61], v[40:41]
	s_nop 1
	v_cndmask_b32_e64 v77, 0, 1, vcc
	v_cmp_gt_u64_e32 vcc, v[60:61], v[42:43]
	s_nop 1
	v_cndmask_b32_e64 v80, 0, 1, vcc
	v_cmp_gt_u64_e32 vcc, v[60:61], v[44:45]
	s_nop 1
	v_cndmask_b32_e64 v81, 0, 1, vcc
	v_cmp_gt_u64_e32 vcc, v[60:61], v[46:47]
	s_nop 1
	v_cndmask_b32_e64 v60, 0, 1, vcc
	v_cmp_gt_u64_e32 vcc, v[62:63], v[32:33]
	s_nop 1
	v_addc_co_u32_e32 v61, vcc, v65, v64, vcc
	v_cmp_gt_u64_e32 vcc, v[62:63], v[34:35]
	s_nop 1
	v_addc_co_u32_e32 v64, vcc, v78, v74, vcc
	v_cmp_gt_u64_e32 vcc, v[62:63], v[36:37]
	s_nop 1
	v_addc_co_u32_e32 v74, vcc, v79, v75, vcc
	v_cmp_gt_u64_e32 vcc, v[62:63], v[38:39]
	s_nop 1
	v_addc_co_u32_e32 v70, vcc, v70, v76, vcc
	v_cmp_gt_u64_e32 vcc, v[62:63], v[40:41]
	s_nop 1
	v_addc_co_u32_e32 v71, vcc, v71, v77, vcc
	v_cmp_gt_u64_e32 vcc, v[62:63], v[42:43]
	s_nop 1
	v_addc_co_u32_e32 v72, vcc, v72, v80, vcc
	v_cmp_gt_u64_e32 vcc, v[62:63], v[44:45]
	s_nop 1
	v_addc_co_u32_e32 v73, vcc, v73, v81, vcc
	v_cmp_gt_u64_e32 vcc, v[62:63], v[46:47]
	s_nop 1
	v_addc_co_u32_e32 v59, vcc, v59, v60, vcc
	s_waitcnt lgkmcnt(0)
	v_cmp_gt_u64_e32 vcc, v[66:67], v[32:33]
	s_nop 1
	v_cndmask_b32_e64 v60, 0, 1, vcc
	v_cmp_gt_u64_e32 vcc, v[66:67], v[34:35]
	s_nop 1
	v_cndmask_b32_e64 v62, 0, 1, vcc
	v_cmp_gt_u64_e32 vcc, v[66:67], v[36:37]
	s_nop 1
	v_cndmask_b32_e64 v63, 0, 1, vcc
	v_cmp_gt_u64_e32 vcc, v[66:67], v[38:39]
	s_nop 1
	v_cndmask_b32_e64 v75, 0, 1, vcc
	v_cmp_gt_u64_e32 vcc, v[66:67], v[40:41]
	s_nop 1
	v_cndmask_b32_e64 v76, 0, 1, vcc
	v_cmp_gt_u64_e32 vcc, v[66:67], v[42:43]
	s_nop 1
	v_cndmask_b32_e64 v77, 0, 1, vcc
	v_cmp_gt_u64_e32 vcc, v[66:67], v[44:45]
	s_nop 1
	v_cndmask_b32_e64 v78, 0, 1, vcc
	v_cmp_gt_u64_e32 vcc, v[66:67], v[46:47]
	s_nop 1
	v_cndmask_b32_e64 v67, 0, 1, vcc
	v_cmp_gt_u64_e32 vcc, v[68:69], v[32:33]
	s_nop 1
	v_addc_co_u32_e32 v66, vcc, v61, v60, vcc
	v_cmp_gt_u64_e32 vcc, v[68:69], v[34:35]
	s_nop 1
	v_addc_co_u32_e32 v65, vcc, v64, v62, vcc
	v_cmp_gt_u64_e32 vcc, v[68:69], v[36:37]
	s_nop 1
	v_addc_co_u32_e32 v64, vcc, v74, v63, vcc
	v_cmp_gt_u64_e32 vcc, v[68:69], v[38:39]
	s_nop 1
	v_addc_co_u32_e32 v63, vcc, v70, v75, vcc
	v_cmp_gt_u64_e32 vcc, v[68:69], v[40:41]
	s_nop 1
	v_addc_co_u32_e32 v62, vcc, v71, v76, vcc
	v_cmp_gt_u64_e32 vcc, v[68:69], v[42:43]
	s_nop 1
	v_addc_co_u32_e32 v61, vcc, v72, v77, vcc
	v_cmp_gt_u64_e32 vcc, v[68:69], v[44:45]
	s_nop 1
	v_addc_co_u32_e32 v60, vcc, v73, v78, vcc
	v_cmp_gt_u64_e32 vcc, v[68:69], v[46:47]
	s_nop 1
	v_addc_co_u32_e32 v59, vcc, v59, v67, vcc
	s_cbranch_scc0 .LBB0_1056
	v_cmp_eq_u32_e32 vcc, 0, v50
	v_cmp_eq_u32_e64 s[6:7], s39, v51
	v_readlane_b32 s8, v255, 2
	s_or_b64 s[0:1], vcc, s[6:7]
	v_cmp_gt_i32_e64 s[6:7], 13, v66
	v_cmp_eq_u32_e32 vcc, s8, v51
	s_or_b64 s[0:1], s[0:1], vcc
	v_cmp_gt_u32_e32 vcc, s8, v51
	v_or_b32_e32 v34, 1, v51
	s_and_b64 s[4:5], vcc, s[6:7]
	s_or_b64 s[0:1], s[0:1], s[4:5]
	v_cmp_ne_u32_e32 vcc, s39, v34
	v_cmp_ne_u32_e64 s[6:7], s8, v34
	v_cndmask_b32_e64 v33, 0, 1, s[0:1]
	s_and_b64 s[0:1], vcc, s[6:7]
	s_and_saveexec_b64 s[4:5], s[0:1]
	s_xor_b64 s[4:5], exec, s[4:5]
	s_cbranch_execz .LBB0_1059
	v_readlane_b32 s0, v255, 2
	v_cmp_gt_i32_e64 s[6:7], 13, v65
	s_nop 0
	v_cmp_gt_u32_e32 vcc, s0, v34
	s_and_b64 s[0:1], vcc, s[6:7]
	v_cndmask_b32_e64 v32, 0, 2, s[0:1]
	v_or_b32_e32 v32, v32, v33
